# non-temporal cache policy on once-read streaming loads: rwpost rows, final-norm rows, prep rmsnorm inputs, attention Q rows
# speedup vs baseline: 1.0050x; 1.0050x over previous
; __device__ __forceinline__ void ph_prep(const Params& p, LAS unsigned char* lds) {
;     ...
;         const int TOT = NTOK + 2048; f32x4 cur[4], nxt[4];
;     ...
;         int row = gw;
;         if (row < TOT) { const f32x4* sp = (const f32x4*)RC_SRC(row);
; #pragma unroll
;             for (int i = 0; i < 4; ++i) cur[i] = sp[i * 64 + lane]; }
.LBB0_29:
	s_or_saveexec_b64 s[4:5], s[4:5]
	v_ashrrev_i32_e32 v33, 31, v32
	s_xor_b64 exec, exec, s[4:5]
	v_mov_b64_e32 v[2:3], v[32:33]
	s_or_b64 exec, exec, s[4:5]
	v_and_b32_e32 v34, 63, v35
	v_lshlrev_b64 v[2:3], 12, v[2:3]
	v_lshl_add_u64 v[0:1], v[0:1], 0, v[2:3]
	v_mov_b32_e32 v37, 0
	v_lshlrev_b32_e32 v36, 4, v34
	v_lshl_add_u64 v[8:9], v[0:1], 0, v[36:37]
	global_load_dwordx4 v[12:15], v[8:9], off nt
	global_load_dwordx4 v[0:3], v[8:9], off offset:1024 nt
	global_load_dwordx4 v[4:7], v[8:9], off offset:2048 nt
	s_nop 0
	global_load_dwordx4 v[8:11], v[8:9], off offset:3072 nt
	v_mbcnt_lo_u32_b32 v16, -1, 0
	v_mbcnt_hi_u32_b32 v16, -1, v16
	v_and_b32_e32 v18, 64, v16
	v_xor_b32_e32 v17, 16, v16
	v_add_u32_e32 v18, 64, v18
	v_cmp_lt_i32_e32 vcc, v17, v18
	s_lshl_b32 s12, s34, 3
	s_mov_b64 s[6:7], 0x1b480000
	v_cndmask_b32_e32 v17, v16, v17, vcc
	v_lshlrev_b32_e32 v44, 2, v17
	v_xor_b32_e32 v17, 32, v16
	v_cmp_lt_i32_e32 vcc, v17, v18
	s_ashr_i32 s13, s12, 31
	v_add_u32_e32 v40, s12, v32
	v_cndmask_b32_e32 v16, v16, v17, vcc
	v_lshlrev_b32_e32 v45, 2, v16
	v_lshl_add_u64 v[16:17], v[32:33], 2, s[92:93]
	v_cmp_eq_u32_e64 s[4:5], 0, v34
	v_lshl_add_u64 v[38:39], v[16:17], 0, s[6:7]
	s_lshl_b64 s[68:69], s[12:13], 2
	v_ashrrev_i32_e32 v41, 31, v40
	s_mov_b64 s[70:71], 0
	s_mov_b32 s3, 0x89ff
	s_movk_i32 s8, 0x7fff
	s_mov_b32 s9, 0x81ff
	s_mov_b32 s14, 0x8200
	v_mov_b32_e32 v46, 0x358637bd
	s_mov_b32 s15, 0x800000
	v_mov_b32_e32 v47, 0x19880000
	v_mov_b32_e32 v48, 0x11680000
	s_mov_b64 s[72:73], 0
	v_mov_b32_e32 v49, v32
	s_branch .LBB0_33

; __device__ __forceinline__ void ph_prep(const Params& p, LAS unsigned char* lds) {
;     ...
;         for (; row < TOT; row += nw) {
;             const int nr = row + nw;
;             if (nr < TOT) { const f32x4* sp = (const f32x4*)RC_SRC(nr);
; #pragma unroll
;                 for (int i = 0; i < 4; ++i) nxt[i] = sp[i * 64 + lane]; }
.LBB0_40:
	s_andn2_saveexec_b64 s[6:7], s[76:77]
	v_lshl_add_u64 v[18:19], v[40:41], 0, s[72:73]
	s_or_b64 exec, exec, s[6:7]
	v_lshlrev_b64 v[18:19], 12, v[18:19]
	v_lshl_add_u64 v[16:17], v[16:17], 0, v[18:19]
	v_lshlrev_b32_e32 v36, 4, v34
	v_lshl_add_u64 v[16:17], v[16:17], 0, v[36:37]
	global_load_dwordx4 v[28:31], v[16:17], off nt
	global_load_dwordx4 v[24:27], v[16:17], off offset:1024 nt
	global_load_dwordx4 v[20:23], v[16:17], off offset:2048 nt
	s_nop 0
	global_load_dwordx4 v[16:19], v[16:17], off offset:3072 nt

; __device__ __forceinline__ int opaque_tid() { int t = threadIdx.x; asm volatile("" : "+v"(t)); return t; }
; __device__ __forceinline__ void ph_rwpost(const Params& p) {
;     const int tid = opaque_tid(), lane = tid & 63, wid = tid >> 6; const int gw = blockIdx.x * 8 + wid, nw = gridDim.x * 8;
;     unsigned char* ws = p.ws; bf16_t* ob = (bf16_t*)(ws + WS_B); const bf16_t* phg = (const bf16_t*)(ws + WS_PHG); const bf16_t* oi = (const bf16_t*)(ws + WS_OI);
;     const bf16_t* kp = (const bf16_t*)(ws + WS_PRW); const bf16_t* gb = (const bf16_t*)(ws + WS_PRW + HALF512); const bf16_t* rb = (const bf16_t*)(ws + WS_A); const bf16_t* vb = (const bf16_t*)(ws + WS_A + HALF512);
;     const int c = lane * 8; float rk[8], gw8[8], gb8[8], hn[8];
; #pragma unroll
;     for (int j = 0; j < 8; ++j) { rk[j] = p.in[20][c + j]; gw8[j] = p.in[21][c + j]; gb8[j] = p.in[22][c + j]; hn[j] = p.in[11][c + j]; }
;     u32x4 cur[7], nxt[7];
;     ...
;     int row = gw;
;     if (row < NTOK) RP_LD(cur, row);
.LBB0_829:
	s_cmp_lt_i32 s94, 6
	s_cselect_b64 s[6:7], -1, 0
	s_and_b64 s[0:1], s[6:7], s[4:5]
	s_andn2_b64 vcc, exec, s[0:1]
	s_cbranch_vccnz .LBB0_836
	s_waitcnt vmcnt(0)
	v_mov_b32_e32 v32, v200
	s_mov_b32 s3, 0x8200
	v_ashrrev_i32_e32 v0, 6, v32
	v_lshl_add_u32 v88, s2, 3, v0
	v_cmp_gt_i32_e32 vcc, s3, v88
	s_and_saveexec_b64 s[4:5], vcc
	s_cbranch_execz .LBB0_835
	v_readlane_b32 s16, v236, 23
	v_lshlrev_b32_e32 v33, 3, v32
	v_readlane_b32 s17, v236, 24
	v_readlane_b32 s18, v236, 25
	v_readlane_b32 s19, v236, 26
	v_readlane_b32 s20, v236, 27
	v_readlane_b32 s21, v236, 28
	v_readlane_b32 s22, v236, 29
	v_readlane_b32 s23, v236, 30
	v_and_b32_e32 v36, 0x1f8, v33
	v_readlane_b32 s8, v236, 7
	v_ashrrev_i32_e32 v89, 31, v88
	v_lshlrev_b32_e32 v34, 2, v36
	v_readlane_b32 s24, v236, 31
	v_readlane_b32 s25, v236, 32
	v_readlane_b32 s14, v236, 13
	v_readlane_b32 s15, v236, 14
	v_lshlrev_b64 v[90:91], 11, v[88:89]
	v_readlane_b32 s26, v236, 33
	v_readlane_b32 s27, v236, 34
	v_readlane_b32 s28, v236, 35
	v_readlane_b32 s29, v236, 36
	global_load_dwordx4 v[0:3], v34, s[24:25]
	s_nop 1
	global_load_dwordx4 v[4:7], v34, s[26:27]
	global_load_dwordx4 v[8:11], v34, s[26:27] offset:16
	global_load_dwordx4 v[12:15], v34, s[28:29] offset:16
	global_load_dwordx4 v[16:19], v34, s[24:25] offset:16
	global_load_dwordx4 v[20:23], v34, s[28:29]
	v_readlane_b32 s10, v236, 9
	v_readlane_b32 s11, v236, 10
	global_load_dwordx4 v[24:27], v34, s[14:15] offset:16
	global_load_dwordx4 v[28:31], v34, s[14:15]
	v_lshl_add_u64 v[34:35], s[92:93], 0, v[90:91]
	v_lshlrev_b32_e32 v36, 1, v36
	v_mov_b32_e32 v37, 0
	s_mov_b64 s[10:11], s[14:15]
	v_lshl_add_u64 v[34:35], v[34:35], 0, v[36:37]
	s_mov_b32 s14, 0x15780000
	v_lshlrev_b64 v[38:39], 10, v[88:89]
	v_add_co_u32_e32 v34, vcc, s14, v34
	v_or_b32_e32 v38, v38, v36
	s_nop 0
	v_addc_co_u32_e32 v35, vcc, 0, v35, vcc
	v_lshl_add_u64 v[38:39], s[92:93], 0, v[38:39]
	s_mov_b32 s0, 0x11680000
	v_add_co_u32_e32 v40, vcc, s0, v38
	s_mov_b32 s0, 0xa4c0000
	s_nop 0
	v_addc_co_u32_e32 v41, vcc, 0, v39, vcc
	global_load_dwordx4 v[68:71], v[34:35], off offset:1024 nt
	global_load_dwordx4 v[80:83], v[40:41], off nt
	v_add_co_u32_e32 v34, vcc, s0, v38
	s_mov_b32 s0, 0x13700000
	s_nop 0
	v_addc_co_u32_e32 v35, vcc, 0, v39, vcc
	v_add_co_u32_e32 v40, vcc, s0, v38
	s_mov_b32 s0, 0xc540000
	s_nop 0
	v_addc_co_u32_e32 v41, vcc, 0, v39, vcc
	global_load_dwordx4 v[84:87], v[34:35], off nt
	global_load_dwordx4 v[72:75], v[40:41], off nt
	v_add_co_u32_e32 v34, vcc, s0, v38
	v_bfe_u32 v33, v33, 5, 4
	s_nop 0
	v_addc_co_u32_e32 v35, vcc, 0, v39, vcc
	v_mul_u32_u24_e32 v38, 0x8200, v33
	v_mov_b32_e32 v39, v37
	v_lshl_add_u64 v[40:41], v[38:39], 0, v[88:89]
	v_lshlrev_b64 v[40:41], 6, v[40:41]
	v_lshlrev_b32_e32 v33, 4, v32
	v_lshl_add_u64 v[40:41], s[92:93], 0, v[40:41]
	v_and_b32_e32 v42, 48, v33
	v_mov_b32_e32 v43, v37
	v_lshl_add_u64 v[40:41], v[40:41], 0, v[42:43]
	s_mov_b32 s0, 0x1b9b6000
	v_add_co_u32_e32 v40, vcc, s0, v40
	s_mov_b32 s0, 0x22c0000
	s_nop 0
	v_addc_co_u32_e32 v41, vcc, 0, v41, vcc
	global_load_dwordx4 v[76:79], v[34:35], off nt
	global_load_dwordx4 v[60:63], v[40:41], off offset:2048 nt
	v_lshlrev_b64 v[34:35], 12, v[88:89]
	v_lshl_add_u64 v[34:35], s[92:93], 0, v[34:35]
	v_lshl_add_u64 v[34:35], v[34:35], 0, v[36:37]
	v_add_co_u32_e32 v34, vcc, s0, v34
	s_lshl_b32 s8, s34, 3
	s_nop 0
	v_addc_co_u32_e32 v35, vcc, 0, v35, vcc
	global_load_dwordx4 v[64:67], v[34:35], off offset:3072 nt
	v_add_u32_e32 v34, s8, v88
	v_ashrrev_i32_e32 v35, 31, v34
	v_and_b32_e32 v40, 0x3f0, v33
	v_lshlrev_b64 v[36:37], 12, v[34:35]
	v_or_b32_e32 v36, v36, v40
	s_mov_b64 s[0:1], 0x22c0c00
	v_lshl_add_u64 v[92:93], v[36:37], 0, s[0:1]
	v_lshl_add_u64 v[36:37], v[34:35], 0, v[38:39]
	v_lshlrev_b64 v[36:37], 6, v[36:37]
	v_and_b32_e32 v32, 3, v32
	v_readlane_b32 s9, v236, 8
	v_readlane_b32 s22, v236, 21
	v_readlane_b32 s23, v236, 22
	v_lshl_or_b32 v36, v32, 4, v36
	s_mov_b64 s[0:1], 0x1b9b6800
	v_lshlrev_b64 v[32:33], 11, v[34:35]
	v_readlane_b32 s12, v236, 11
	v_readlane_b32 s13, v236, 12
	v_readlane_b32 s16, v236, 15
	v_readlane_b32 s17, v236, 16
	v_readlane_b32 s18, v236, 17
	v_readlane_b32 s19, v236, 18
	v_readlane_b32 s20, v236, 19
	v_readlane_b32 s21, v236, 20
	s_ashr_i32 s9, s8, 31
	v_lshl_add_u64 v[94:95], v[36:37], 0, s[0:1]
	v_or_b32_e32 v32, v32, v40
	s_mov_b64 s[0:1], 0x15780400
	v_lshlrev_b64 v[98:99], 10, v[34:35]
	s_brev_b32 s22, 60
	v_or_b32_e32 v90, v90, v40
	s_lshl_b64 s[10:11], s[8:9], 11
	s_lshl_b64 s[12:13], s[8:9], 12
	s_lshl_b64 s[16:17], s[8:9], 6
	v_lshl_add_u64 v[96:97], v[32:33], 0, s[0:1]
	v_or_b32_e32 v98, v98, v40
	s_lshl_b64 s[18:19], s[8:9], 10
	s_mov_b64 s[20:21], 0
	s_mov_b32 s9, 0x81ff
	s_mov_b32 s23, 0x3c800000
	s_mov_b32 s15, 0x800000
	v_mov_b32_e32 v100, 0x358637bd
	v_mov_b32_e32 v101, 0x3a27c5ac
	v_readlane_b32 s30, v236, 37
	v_readlane_b32 s31, v236, 38
	s_branch .LBB0_833

; __device__ __forceinline__ void ph_rwpost(const Params& p) {
;     ...
; #pragma unroll 1
;     for (; row < NTOK; row += nw) {
;         const int nr = row + nw;
;         if (nr < NTOK) RP_LD(nxt, nr);
.LBB0_833:
	v_add_u32_e32 v88, s8, v88
	v_cmp_lt_i32_e64 s[0:1], s9, v88
	v_cmp_gt_i32_e32 vcc, s3, v88
	s_or_b64 s[20:21], s[0:1], s[20:21]
	s_and_saveexec_b64 s[0:1], vcc
	s_cbranch_execz .LBB0_832
	v_lshl_add_u64 v[48:49], s[92:93], 0, v[98:99]
	v_add_co_u32_e32 v42, vcc, 0x11680000, v48
	v_lshl_add_u64 v[40:41], s[92:93], 0, v[96:97]
	s_nop 0
	v_addc_co_u32_e32 v43, vcc, 0, v49, vcc
	v_add_co_u32_e32 v50, vcc, 0xa4c0000, v48
	global_load_dwordx4 v[32:35], v[40:41], off nt
	global_load_dwordx4 v[36:39], v[42:43], off nt
	v_addc_co_u32_e32 v51, vcc, 0, v49, vcc
	v_add_co_u32_e32 v52, vcc, 0x13700000, v48
	v_lshl_add_u64 v[58:59], s[92:93], 0, v[94:95]
	s_nop 0
	v_addc_co_u32_e32 v53, vcc, 0, v49, vcc
	v_add_co_u32_e32 v56, vcc, 0xc540000, v48
	global_load_dwordx4 v[40:43], v[50:51], off nt
	global_load_dwordx4 v[44:47], v[52:53], off nt
	v_addc_co_u32_e32 v57, vcc, 0, v49, vcc
	global_load_dwordx4 v[48:51], v[56:57], off nt
	global_load_dwordx4 v[52:55], v[58:59], off nt
	v_lshl_add_u64 v[56:57], s[92:93], 0, v[92:93]
	global_load_dwordx4 v[56:59], v[56:57], off nt
	s_branch .LBB0_832

; __device__ __forceinline__ void ph_attn(const Params& p, LAS unsigned char* lds) {
;     ...
;         if (active) {
;             const bf16_t* qp = qb + (size_t)(r0 + w * 16 + fr) * D + h * 256 + fq * 8;
; #pragma unroll
;             for (int ks = 0; ks < 8; ++ks) qf[ks] = *(const bf16x8*)(qp + ks * 32);
;         }
.LBB0_1090:
	v_add_u32_e32 v190, s18, v196
	s_andn2_b64 vcc, exec, s[16:17]
	v_ashrrev_i32_e32 v191, 31, v190
	s_cbranch_vccnz .LBB0_1092
	s_add_i32 s16, s18, s21
	v_lshrrev_b32_e32 v204, 5, v203
	v_add_u32_e32 v204, s16, v204
	v_lshlrev_b32_e32 v204, 11, v204
	s_lshl_b32 s16, s5, 9
	v_and_b32_e32 v2, 31, v203
	v_lshlrev_b32_e32 v2, 4, v2
	v_add3_u32 v204, v204, s16, v2
	s_cmp_eq_u32 s96, 1
	s_cbranch_scc1 .Lpf_skipq
	v_mov_b32_e32 v32, v204
	v_add_u32_e32 v28, 0x1000, v204
	v_add_u32_e32 v24, 0x2000, v204
	v_add_u32_e32 v20, 0x3000, v204
	v_add_u32_e32 v16, 0x4000, v204
	v_add_u32_e32 v12, 0x5000, v204
	v_add_u32_e32 v8, 0x6000, v204
	v_add_u32_e32 v4, 0x7000, v204
	global_load_dwordx4 v[32:35], v32, s[6:7] nt
	global_load_dwordx4 v[28:31], v28, s[6:7] nt
	global_load_dwordx4 v[24:27], v24, s[6:7] nt
	global_load_dwordx4 v[20:23], v20, s[6:7] nt
	global_load_dwordx4 v[16:19], v16, s[6:7] nt
	global_load_dwordx4 v[12:15], v12, s[6:7] nt
	global_load_dwordx4 v[8:11], v8, s[6:7] nt
	global_load_dwordx4 v[4:7], v4, s[6:7] nt

; #define LAS __attribute__((address_space(3)))
; #define LOADV(i) do { _Pragma("unroll") for (int j = 0; j < 4; ++j) st[j] = *(const u32x4*)(vbase + (j * 64 * 256 + (i) * 64) + voff); } while (0)
; #define STOREV() do { _Pragma("unroll") for (int j = 0; j < 4; ++j) *(LAS u32x4*)(vst + j * 64 * 144) = st[j]; } while (0)
; __device__ __forceinline__ void ph_attn(const Params& p, LAS unsigned char* lds) {
;     ...
;         if (active) {
;             const bf16_t* qp = qb + (size_t)(r0 + w * 16 + fr) * D + h * 256 + fq * 8;
; #pragma unroll
;             for (int ks = 0; ks < 8; ++ks) qf[ks] = *(const bf16x8*)(qp + ks * 32);
;     ...
; #pragma unroll 1
;         for (int i = 0; i < 4; ++i) {
;             __syncthreads(); STOREV(); __syncthreads();
;             if (i < 3) LOADV(i + 1);
;             if (active) {
; #pragma unroll
;                 for (int ks = 0; ks < 2; ++ks) {
;                     const bf16x8 pf = *(const LAS bf16x8*)(pw + fq * 8 + i * 128 + ks * 64);
; #pragma unroll
;                     for (int dt = 0; dt < 16; ++dt) {
;                         const bf16x8 vf = *(const LAS bf16x8*)(vrd + dt * 16 * 144 + ks * 64);
;                         oa[dt] = __builtin_amdgcn_mfma_f32_16x16x32_bf16(vf, pf, oa[dt], 0, 0, 0);
;                     }
;                 }
;             }
;         }
.Lat_pv1:
	s_waitcnt lgkmcnt(0)
	s_barrier
	s_waitcnt vmcnt(7)
	ds_write_b128 v199, v[240:243]
	s_waitcnt vmcnt(6)
	ds_write_b128 v199, v[244:247] offset:8192
	s_waitcnt vmcnt(5)
	ds_write_b128 v199, v[248:251] offset:16384
	s_waitcnt vmcnt(4)
	ds_write_b128 v199, v[252:255] offset:24576
	v_mov_b32_e32 v240, v238
	v_add_u32_e32 v244, 0x8000, v238
	v_add_u32_e32 v248, 0x10000, v238
	v_add_u32_e32 v252, 0x18000, v238
	s_waitcnt lgkmcnt(0)
	s_barrier
	global_load_dwordx4 v[240:243], v240, s[100:101] offset:384
	global_load_dwordx4 v[244:247], v244, s[100:101] offset:384
	global_load_dwordx4 v[248:251], v248, s[100:101] offset:384
	global_load_dwordx4 v[252:255], v252, s[100:101] offset:384
	s_add_i32 s97, s27, s34
	s_cmpk_lt_i32 s97, 0x400
	s_cselect_b32 s96, 1, 0
	s_cmpk_lg_i32 s34, 0x100
	s_cselect_b32 s96, 0, s96
	s_cmp_eq_u32 s96, 0
	s_cbranch_scc1 .Lpf_noq
	v_add_u32_e32 v32, 0x1000000, v204
	v_add_u32_e32 v28, 0x1001000, v204
	v_add_u32_e32 v24, 0x1002000, v204
	v_add_u32_e32 v20, 0x1003000, v204
	v_add_u32_e32 v16, 0x1004000, v204
	v_add_u32_e32 v12, 0x1005000, v204
	v_add_u32_e32 v8, 0x1006000, v204
	v_add_u32_e32 v4, 0x1007000, v204
	global_load_dwordx4 v[32:35], v32, s[6:7] nt
	global_load_dwordx4 v[28:31], v28, s[6:7] nt
	global_load_dwordx4 v[24:27], v24, s[6:7] nt
	global_load_dwordx4 v[20:23], v20, s[6:7] nt
	global_load_dwordx4 v[16:19], v16, s[6:7] nt
	global_load_dwordx4 v[12:15], v12, s[6:7] nt
	global_load_dwordx4 v[8:11], v8, s[6:7] nt
	global_load_dwordx4 v[4:7], v4, s[6:7] nt
	.Lpf_noq:
	s_and_b64 vcc, exec, s[4:5]
	s_cbranch_vccnz .Lat_pv2
	ds_read_b128 v[208:211], v187 offset:128
	ds_read_b128 v[212:215], v187 offset:192
	ds_read_b128 v[36:39], v201
	ds_read_b128 v[40:43], v201 offset:2048
	ds_read_b128 v[44:47], v201 offset:4096
	ds_read_b128 v[48:51], v201 offset:6144
	ds_read_b128 v[52:55], v201 offset:8192
	ds_read_b128 v[56:59], v201 offset:10240
	ds_read_b128 v[60:63], v201 offset:12288
	ds_read_b128 v[64:67], v201 offset:14336
	s_waitcnt lgkmcnt(7)
	v_mfma_f32_16x16x32_bf16 v[176:179], v[36:39], v[208:211], v[176:179]
	ds_read_b128 v[68:71], v201 offset:16384
	s_waitcnt lgkmcnt(7)
	v_mfma_f32_16x16x32_bf16 v[172:175], v[40:43], v[208:211], v[172:175]
	ds_read_b128 v[72:75], v201 offset:18432
	s_waitcnt lgkmcnt(7)
	v_mfma_f32_16x16x32_bf16 v[168:171], v[44:47], v[208:211], v[168:171]
	ds_read_b128 v[76:79], v201 offset:20480
	s_waitcnt lgkmcnt(7)
	v_mfma_f32_16x16x32_bf16 v[164:167], v[48:51], v[208:211], v[164:167]
	ds_read_b128 v[80:83], v201 offset:22528
	s_waitcnt lgkmcnt(7)
	v_mfma_f32_16x16x32_bf16 v[160:163], v[52:55], v[208:211], v[160:163]
	ds_read_b128 v[84:87], v201 offset:24576
	s_waitcnt lgkmcnt(7)
	v_mfma_f32_16x16x32_bf16 v[156:159], v[56:59], v[208:211], v[156:159]
	ds_read_b128 v[88:91], v201 offset:26624
	s_waitcnt lgkmcnt(7)
	v_mfma_f32_16x16x32_bf16 v[152:155], v[60:63], v[208:211], v[152:155]
	ds_read_b128 v[92:95], v201 offset:28672
	s_waitcnt lgkmcnt(7)
	v_mfma_f32_16x16x32_bf16 v[148:151], v[64:67], v[208:211], v[148:151]
	ds_read_b128 v[96:99], v201 offset:30720
	s_waitcnt lgkmcnt(7)
	v_mfma_f32_16x16x32_bf16 v[144:147], v[68:71], v[208:211], v[144:147]
	ds_read_b128 v[36:39], v239
	s_waitcnt lgkmcnt(7)
	v_mfma_f32_16x16x32_bf16 v[140:143], v[72:75], v[208:211], v[140:143]
	ds_read_b128 v[40:43], v239 offset:2048
	s_waitcnt lgkmcnt(7)
	v_mfma_f32_16x16x32_bf16 v[136:139], v[76:79], v[208:211], v[136:139]
	ds_read_b128 v[44:47], v239 offset:4096
	s_waitcnt lgkmcnt(7)
	v_mfma_f32_16x16x32_bf16 v[132:135], v[80:83], v[208:211], v[132:135]
	ds_read_b128 v[48:51], v239 offset:6144
	s_waitcnt lgkmcnt(7)
	v_mfma_f32_16x16x32_bf16 v[128:131], v[84:87], v[208:211], v[128:131]
	ds_read_b128 v[52:55], v239 offset:8192
	s_waitcnt lgkmcnt(7)
	v_mfma_f32_16x16x32_bf16 v[124:127], v[88:91], v[208:211], v[124:127]
	ds_read_b128 v[56:59], v239 offset:10240
	s_waitcnt lgkmcnt(7)
	v_mfma_f32_16x16x32_bf16 v[120:123], v[92:95], v[208:211], v[120:123]
	ds_read_b128 v[60:63], v239 offset:12288
	s_waitcnt lgkmcnt(7)
	v_mfma_f32_16x16x32_bf16 v[116:119], v[96:99], v[208:211], v[116:119]
	ds_read_b128 v[64:67], v239 offset:14336
	s_waitcnt lgkmcnt(7)
	v_mfma_f32_16x16x32_bf16 v[176:179], v[36:39], v[212:215], v[176:179]
	ds_read_b128 v[68:71], v239 offset:16384
	s_waitcnt lgkmcnt(7)
	v_mfma_f32_16x16x32_bf16 v[172:175], v[40:43], v[212:215], v[172:175]
	ds_read_b128 v[72:75], v239 offset:18432
	s_waitcnt lgkmcnt(7)
	v_mfma_f32_16x16x32_bf16 v[168:171], v[44:47], v[212:215], v[168:171]
	ds_read_b128 v[76:79], v239 offset:20480
	s_waitcnt lgkmcnt(7)
	v_mfma_f32_16x16x32_bf16 v[164:167], v[48:51], v[212:215], v[164:167]
	ds_read_b128 v[80:83], v239 offset:22528
	s_waitcnt lgkmcnt(7)
	v_mfma_f32_16x16x32_bf16 v[160:163], v[52:55], v[212:215], v[160:163]
	ds_read_b128 v[84:87], v239 offset:24576
	s_waitcnt lgkmcnt(7)
	v_mfma_f32_16x16x32_bf16 v[156:159], v[56:59], v[212:215], v[156:159]
	ds_read_b128 v[88:91], v239 offset:26624
	s_waitcnt lgkmcnt(7)
	v_mfma_f32_16x16x32_bf16 v[152:155], v[60:63], v[212:215], v[152:155]
	ds_read_b128 v[92:95], v239 offset:28672
	s_waitcnt lgkmcnt(7)
	v_mfma_f32_16x16x32_bf16 v[148:151], v[64:67], v[212:215], v[148:151]
	ds_read_b128 v[96:99], v239 offset:30720
	s_waitcnt lgkmcnt(7)
	v_mfma_f32_16x16x32_bf16 v[144:147], v[68:71], v[212:215], v[144:147]
	s_waitcnt lgkmcnt(6)
	v_mfma_f32_16x16x32_bf16 v[140:143], v[72:75], v[212:215], v[140:143]
	s_waitcnt lgkmcnt(5)
	v_mfma_f32_16x16x32_bf16 v[136:139], v[76:79], v[212:215], v[136:139]
	s_waitcnt lgkmcnt(4)
	v_mfma_f32_16x16x32_bf16 v[132:135], v[80:83], v[212:215], v[132:135]
	s_waitcnt lgkmcnt(3)
	v_mfma_f32_16x16x32_bf16 v[128:131], v[84:87], v[212:215], v[128:131]
	s_waitcnt lgkmcnt(2)
	v_mfma_f32_16x16x32_bf16 v[124:127], v[88:91], v[212:215], v[124:127]
	s_waitcnt lgkmcnt(1)
	v_mfma_f32_16x16x32_bf16 v[120:123], v[92:95], v[212:215], v[120:123]
	s_waitcnt lgkmcnt(0)
	v_mfma_f32_16x16x32_bf16 v[116:119], v[96:99], v[212:215], v[116:119]

; __device__ __forceinline__ int opaque_tid() { int t = threadIdx.x; asm volatile("" : "+v"(t)); return t; }
; __device__ __forceinline__ void ph_final(const Params& p) {
;     const int tid = opaque_tid(), lane = tid & 63, wid = tid >> 6; const int gw = blockIdx.x * 8 + wid, nw = gridDim.x * 8;
;     f32x4 gn[4], cur[4], nxt[4];
; #pragma unroll
;     for (int i = 0; i < 4; ++i) gn[i] = ((const f32x4*)p.in[34])[i * 64 + lane];
;     int row = gw;
;     if (row < NTOK) { const f32x4* x = (const f32x4*)(p.out + (size_t)row * D);
; #pragma unroll
;         for (int i = 0; i < 4; ++i) cur[i] = x[i * 64 + lane]; }
.LBB0_1433:
	s_cmp_lt_i32 s94, 13
	s_cselect_b64 s[4:5], -1, 0
	s_and_b64 s[0:1], s[4:5], s[0:1]
	s_andn2_b64 vcc, exec, s[0:1]
	s_cbranch_vccnz .LBB0_1439
	s_mov_b32 s10, 0x8200
	v_ashrrev_i32_e32 v0, 6, v200
	v_lshl_add_u32 v48, s2, 3, v0
	v_cmp_gt_i32_e32 vcc, s10, v48
	s_and_saveexec_b64 s[0:1], vcc
	s_cbranch_execz .LBB0_1439
	v_ashrrev_i32_e32 v49, 31, v48
	v_and_b32_e32 v0, 63, v200
	s_waitcnt vmcnt(0)
	v_lshlrev_b64 v[16:17], 12, v[48:49]
	v_lshlrev_b32_e32 v50, 4, v0
	v_mov_b32_e32 v51, 0
	v_lshl_add_u64 v[52:53], s[90:91], 0, v[16:17]
	v_lshl_add_u64 v[32:33], v[52:53], 0, v[50:51]
	s_waitcnt lgkmcnt(0)
	global_load_dwordx4 v[0:3], v50, s[88:89]
	global_load_dwordx4 v[4:7], v50, s[88:89] offset:1024
	global_load_dwordx4 v[8:11], v50, s[88:89] offset:2048
	global_load_dwordx4 v[12:15], v50, s[88:89] offset:3072
	global_load_dwordx4 v[28:31], v[32:33], off nt
	global_load_dwordx4 v[24:27], v[32:33], off offset:1024 nt
	global_load_dwordx4 v[20:23], v[32:33], off offset:2048 nt
	global_load_dwordx4 v[16:19], v[32:33], off offset:3072 nt
	v_mbcnt_lo_u32_b32 v32, -1, 0
	v_mbcnt_hi_u32_b32 v32, -1, v32
	v_and_b32_e32 v34, 64, v32
	v_xor_b32_e32 v33, 16, v32
	v_add_u32_e32 v34, 64, v34
	v_cmp_lt_i32_e32 vcc, v33, v34
	s_lshl_b32 s2, s34, 3
	s_ashr_i32 s3, s2, 31
	v_cndmask_b32_e32 v33, v32, v33, vcc
	v_lshlrev_b32_e32 v49, 2, v33
	v_xor_b32_e32 v33, 32, v32
	v_cmp_lt_i32_e32 vcc, v33, v34
	s_lshl_b64 s[4:5], s[2:3], 12
	s_mov_b64 s[6:7], 0
	v_cndmask_b32_e32 v32, v32, v33, vcc
	v_lshlrev_b32_e32 v56, 2, v32
	v_add_u32_e32 v32, s2, v48
	v_ashrrev_i32_e32 v33, 31, v32
	v_lshlrev_b64 v[32:33], 12, v[32:33]
	v_lshl_add_u64 v[54:55], s[90:91], 0, v[32:33]
	s_mov_b32 s3, 0x81ff
	v_mov_b32_e32 v57, 0x358637bd
	s_mov_b32 s11, 0x800000
	v_mov_b32_e32 v32, v51
	v_mov_b32_e32 v33, v51
	v_mov_b32_e32 v34, v51
	v_mov_b32_e32 v35, v51
	v_mov_b32_e32 v36, v51
	v_mov_b32_e32 v37, v51
	v_mov_b32_e32 v38, v51
	v_mov_b32_e32 v39, v51
	v_mov_b32_e32 v40, v51
	v_mov_b32_e32 v41, v51
	v_mov_b32_e32 v42, v51
	v_mov_b32_e32 v43, v51
	v_mov_b32_e32 v44, v51
	v_mov_b32_e32 v45, v51
	v_mov_b32_e32 v46, v51
	v_mov_b32_e32 v47, v51
	s_branch .LBB0_1437

; __device__ __forceinline__ void ph_final(const Params& p) {
;     ...
; #pragma unroll 1
;     for (; row < NTOK; row += nw) {
;         const int nr = row + nw;
;         if (nr < NTOK) { const f32x4* x = (const f32x4*)(p.out + (size_t)nr * D);
; #pragma unroll
;             for (int i = 0; i < 4; ++i) nxt[i] = x[i * 64 + lane]; }
.LBB0_1437:
	v_add_u32_e32 v48, s2, v48
	v_cmp_gt_i32_e64 s[0:1], s10, v48
	v_cmp_lt_i32_e32 vcc, s3, v48
	s_and_saveexec_b64 s[8:9], s[0:1]
	s_cbranch_execz .LBB0_1436
	v_lshl_add_u64 v[58:59], v[54:55], 0, v[50:51]
	global_load_dwordx4 v[32:35], v[58:59], off nt
	global_load_dwordx4 v[36:39], v[58:59], off offset:1024 nt
	global_load_dwordx4 v[40:43], v[58:59], off offset:2048 nt
	global_load_dwordx4 v[44:47], v[58:59], off offset:3072 nt
	s_branch .LBB0_1436
